# RWKV prompt loop: decay/a LoRA block of waves 0-3 for the next chunk moved to the start of the recurrence segment (runs beside the partner waves recurrence)
# baseline (speedup 1.0000x reference)
.LBB0_1232:
	s_andn2_saveexec_b64 s[22:23], s[22:23]
	s_cbranch_execz .LBB0_1234
	s_cmp_lg_u32 s4, 0
	s_cbranch_scc1 .LBB0_1234

.LBB0_1238:
	s_or_b64 exec, exec, s[18:19]
	s_waitcnt lgkmcnt(0)
	s_barrier
	s_cmpk_eq_i32 s4, 0x7f
	s_cbranch_scc1 .Lrw_nob
	s_mov_b64 s[22:23], exec
	s_andn2_b64 exec, exec, s[6:7]
	s_cbranch_execz .Lrw_nob1
	s_waitcnt vmcnt(0)
	v_mfma_f32_16x16x32_bf16 v[56:59], v[0:3], v[32:35], 0
	v_mfma_f32_16x16x32_bf16 v[56:59], v[4:7], v[36:39], v[56:59]
	v_mfma_f32_16x16x32_bf16 v[60:63], v[8:11], v[40:43], 0
	v_mfma_f32_16x16x32_bf16 v[60:63], v[12:15], v[44:47], v[60:63]
	s_nop 5
	v_add_f32_e32 v57, v17, v57
	v_mul_f32_e32 v57, 0xbfb8aa3b, v57
	v_add_f32_e32 v56, v16, v56
	v_exp_f32_e32 v57, v57
	v_mul_f32_e32 v56, 0xbfb8aa3b, v56
	v_exp_f32_e32 v56, v56
	v_add_f32_e32 v60, v20, v60
	v_add_f32_e32 v57, 1.0, v57
	v_add_f32_e32 v58, v18, v58
	v_mul_f32_e32 v60, 0xbfb8aa3b, v60
	v_rcp_f32_e32 v57, v57
	v_mul_f32_e32 v58, 0xbfb8aa3b, v58
	v_add_f32_e32 v61, v21, v61
	v_exp_f32_e32 v60, v60
	v_add_f32_e32 v56, 1.0, v56
	v_exp_f32_e32 v58, v58
	v_mul_f32_e32 v61, 0xbfb8aa3b, v61
	v_rcp_f32_e32 v64, v56
	v_exp_f32_e32 v61, v61
	v_mul_f32_e32 v57, 0xbf1b4598, v57
	v_add_f32_e32 v59, v19, v59
	v_add_f32_e32 v60, 1.0, v60
	v_mul_f32_e32 v57, 0x3fb8aa3b, v57
	v_add_f32_e32 v58, 1.0, v58
	v_mul_f32_e32 v59, 0xbfb8aa3b, v59
	v_rcp_f32_e32 v56, v60
	v_mul_f32_e32 v60, 0xbf1b4598, v64
	v_rcp_f32_e32 v58, v58
	v_exp_f32_e32 v64, v57
	v_add_f32_e32 v57, 1.0, v61
	v_exp_f32_e32 v59, v59
	v_add_f32_e32 v61, v22, v62
	v_mul_f32_e32 v61, 0xbfb8aa3b, v61
	v_exp_f32_e32 v61, v61
	v_mul_f32_e32 v58, 0xbf1b4598, v58
	v_add_f32_e32 v59, 1.0, v59
	v_rcp_f32_e32 v59, v59
	v_mul_f32_e32 v58, 0x3fb8aa3b, v58
	v_exp_f32_e32 v62, v58
	v_add_f32_e32 v58, 1.0, v61
	v_add_f32_e32 v61, v23, v63
	v_mul_f32_e32 v61, 0xbfb8aa3b, v61
	v_exp_f32_e32 v61, v61
	v_mul_f32_e32 v59, 0xbf1b4598, v59
	v_mul_f32_e32 v60, 0x3fb8aa3b, v60
	v_mul_f32_e32 v59, 0x3fb8aa3b, v59
	v_exp_f32_e32 v60, v60
	v_exp_f32_e32 v63, v59
	v_add_f32_e32 v59, 1.0, v61
	v_rcp_f32_e32 v57, v57
	v_rcp_f32_e32 v58, v58
	v_rcp_f32_e32 v59, v59
	v_cvt_pk_f16_f32 v61, v62, v63
	v_cvt_pk_f16_f32 v60, v60, v64
	s_cmp_lg_u32 s100, 0
	s_cselect_b32 s97, 0, 0x800
	v_add_u32_e32 v168, s97, v109
	ds_write_b64 v168, v[60:61] offset:28928
	ds_write_b128 v122, v[56:59] offset:33024
.Lrw_nob1:
	s_mov_b64 exec, s[22:23]
.Lrw_nob:
	s_cmp_lg_u32 s100, 0
	s_cselect_b32 s97, 0x800, 0
	v_add_u32_e32 v167, s97, v114
	ds_read_b128 v[72:75], v114 offset:41216
	ds_read_b128 v[68:71], v114 offset:45312
	ds_read_b128 v[64:67], v114 offset:49408
	ds_read_b128 v[56:59], v114 offset:53504
	ds_read_b128 v[60:63], v167 offset:28928
	ds_read_b32 v85, v115
	s_waitcnt lgkmcnt(0)
	v_dot2_f32_f16 v151, v127, v72, 0
	v_dot2_f32_f16 v151, v126, v73, v151
	v_dot2_f32_f16 v151, v125, v74, v151
	v_dot2_f32_f16 v151, v124, v75, v151
	ds_read_b128 v[134:137], v114 offset:41344
	ds_read_b128 v[138:141], v114 offset:45440
	ds_read_b128 v[142:145], v114 offset:49536
	v_add_f32_dpp v151, v151, v151 quad_perm:[1,0,3,2] row_mask:0xf bank_mask:0xf bound_ctrl:1
	ds_read_b128 v[130:133], v167 offset:29056
	ds_read_b128 v[146:149], v114 offset:53632
	v_add_f32_dpp v151, v151, v151 quad_perm:[2,3,0,1] row_mask:0xf bank_mask:0xf bound_ctrl:1
	ds_read_b32 v160, v115 offset:256
	s_nop 0
	v_add_f32_dpp v151, v151, v151 row_half_mirror row_mask:0xf bank_mask:0xf bound_ctrl:1
	v_cvt_pkrtz_f16_f32 v152, -v151, -v151
	v_pk_mul_f16 v153, v152, v68
	v_pk_mul_f16 v154, v152, v69
	v_pk_mul_f16 v155, v152, v70
	v_pk_mul_f16 v156, v152, v71
	v_pk_fma_f16 v153, v85, v64, v153
	v_pk_fma_f16 v154, v85, v65, v154
	v_pk_fma_f16 v155, v85, v66, v155
	v_pk_fma_f16 v156, v85, v67, v156
	v_pk_fma_f16 v127, v127, v60, v153
	v_pk_fma_f16 v126, v126, v61, v154
	v_pk_fma_f16 v125, v125, v62, v155
	v_pk_fma_f16 v124, v124, v63, v156
	v_dot2_f32_f16 v157, v127, v56, 0
	v_dot2_f32_f16 v157, v126, v57, v157
	v_dot2_f32_f16 v157, v125, v58, v157
	v_dot2_f32_f16 v157, v124, v59, v157
	s_waitcnt lgkmcnt(0)
	v_dot2_f32_f16 v151, v127, v134, 0
	v_dot2_f32_f16 v151, v126, v135, v151
	v_dot2_f32_f16 v151, v125, v136, v151
	v_dot2_f32_f16 v151, v124, v137, v151
	ds_read_b128 v[72:75], v114 offset:41472
	ds_read_b128 v[68:71], v114 offset:45568
	ds_read_b128 v[64:67], v114 offset:49664
	v_add_f32_dpp v151, v151, v151 quad_perm:[1,0,3,2] row_mask:0xf bank_mask:0xf bound_ctrl:1
	ds_read_b128 v[60:63], v167 offset:29184
	ds_read_b128 v[56:59], v114 offset:53760
	v_add_f32_dpp v151, v151, v151 quad_perm:[2,3,0,1] row_mask:0xf bank_mask:0xf bound_ctrl:1
	ds_read_b32 v85, v115 offset:512
	ds_write_b32 v116, v157 offset:0
	v_add_f32_dpp v151, v151, v151 row_half_mirror row_mask:0xf bank_mask:0xf bound_ctrl:1
	v_cvt_pkrtz_f16_f32 v152, -v151, -v151
	v_pk_mul_f16 v153, v152, v138
	v_pk_mul_f16 v154, v152, v139
	v_pk_mul_f16 v155, v152, v140
	v_pk_mul_f16 v156, v152, v141
	v_pk_fma_f16 v153, v160, v142, v153
	v_pk_fma_f16 v154, v160, v143, v154
	v_pk_fma_f16 v155, v160, v144, v155
	v_pk_fma_f16 v156, v160, v145, v156
	v_pk_fma_f16 v127, v127, v130, v153
	v_pk_fma_f16 v126, v126, v131, v154
	v_pk_fma_f16 v125, v125, v132, v155
	v_pk_fma_f16 v124, v124, v133, v156
	v_dot2_f32_f16 v158, v127, v146, 0
	v_dot2_f32_f16 v158, v126, v147, v158
	v_dot2_f32_f16 v158, v125, v148, v158
	v_dot2_f32_f16 v158, v124, v149, v158
	s_waitcnt lgkmcnt(0)
	v_dot2_f32_f16 v151, v127, v72, 0
	v_dot2_f32_f16 v151, v126, v73, v151
	v_dot2_f32_f16 v151, v125, v74, v151
	v_dot2_f32_f16 v151, v124, v75, v151
	ds_read_b128 v[134:137], v114 offset:41600
	ds_read_b128 v[138:141], v114 offset:45696
	ds_read_b128 v[142:145], v114 offset:49792
	v_add_f32_dpp v151, v151, v151 quad_perm:[1,0,3,2] row_mask:0xf bank_mask:0xf bound_ctrl:1
	ds_read_b128 v[130:133], v167 offset:29312
	ds_read_b128 v[146:149], v114 offset:53888
	v_add_f32_dpp v151, v151, v151 quad_perm:[2,3,0,1] row_mask:0xf bank_mask:0xf bound_ctrl:1
	ds_read_b32 v160, v115 offset:768
	ds_write_b32 v116, v158 offset:2048
	v_add_f32_dpp v151, v151, v151 row_half_mirror row_mask:0xf bank_mask:0xf bound_ctrl:1
	v_cvt_pkrtz_f16_f32 v152, -v151, -v151
	v_pk_mul_f16 v153, v152, v68
	v_pk_mul_f16 v154, v152, v69
	v_pk_mul_f16 v155, v152, v70
	v_pk_mul_f16 v156, v152, v71
	v_pk_fma_f16 v153, v85, v64, v153
	v_pk_fma_f16 v154, v85, v65, v154
	v_pk_fma_f16 v155, v85, v66, v155
	v_pk_fma_f16 v156, v85, v67, v156
	v_pk_fma_f16 v127, v127, v60, v153
	v_pk_fma_f16 v126, v126, v61, v154
	v_pk_fma_f16 v125, v125, v62, v155
	v_pk_fma_f16 v124, v124, v63, v156
	v_dot2_f32_f16 v157, v127, v56, 0
	v_dot2_f32_f16 v157, v126, v57, v157
	v_dot2_f32_f16 v157, v125, v58, v157
	v_dot2_f32_f16 v157, v124, v59, v157
	s_waitcnt lgkmcnt(0)
	v_dot2_f32_f16 v151, v127, v134, 0
	v_dot2_f32_f16 v151, v126, v135, v151
	v_dot2_f32_f16 v151, v125, v136, v151
	v_dot2_f32_f16 v151, v124, v137, v151
	ds_read_b128 v[72:75], v114 offset:41728
	ds_read_b128 v[68:71], v114 offset:45824
	ds_read_b128 v[64:67], v114 offset:49920
	v_add_f32_dpp v151, v151, v151 quad_perm:[1,0,3,2] row_mask:0xf bank_mask:0xf bound_ctrl:1
	ds_read_b128 v[60:63], v167 offset:29440
	ds_read_b128 v[56:59], v114 offset:54016
	v_add_f32_dpp v151, v151, v151 quad_perm:[2,3,0,1] row_mask:0xf bank_mask:0xf bound_ctrl:1
	ds_read_b32 v85, v115 offset:1024
	ds_write_b32 v116, v157 offset:4096
	v_add_f32_dpp v151, v151, v151 row_half_mirror row_mask:0xf bank_mask:0xf bound_ctrl:1
	v_cvt_pkrtz_f16_f32 v152, -v151, -v151
	v_pk_mul_f16 v153, v152, v138
	v_pk_mul_f16 v154, v152, v139
	v_pk_mul_f16 v155, v152, v140
	v_pk_mul_f16 v156, v152, v141
	v_pk_fma_f16 v153, v160, v142, v153
	v_pk_fma_f16 v154, v160, v143, v154
	v_pk_fma_f16 v155, v160, v144, v155
	v_pk_fma_f16 v156, v160, v145, v156
	v_pk_fma_f16 v127, v127, v130, v153
	v_pk_fma_f16 v126, v126, v131, v154
	v_pk_fma_f16 v125, v125, v132, v155
	v_pk_fma_f16 v124, v124, v133, v156
	v_dot2_f32_f16 v158, v127, v146, 0
	v_dot2_f32_f16 v158, v126, v147, v158
	v_dot2_f32_f16 v158, v125, v148, v158
	v_dot2_f32_f16 v158, v124, v149, v158
	s_waitcnt lgkmcnt(0)
	v_dot2_f32_f16 v151, v127, v72, 0
	v_dot2_f32_f16 v151, v126, v73, v151
	v_dot2_f32_f16 v151, v125, v74, v151
	v_dot2_f32_f16 v151, v124, v75, v151
	ds_read_b128 v[134:137], v114 offset:41856
	ds_read_b128 v[138:141], v114 offset:45952
	ds_read_b128 v[142:145], v114 offset:50048
	v_add_f32_dpp v151, v151, v151 quad_perm:[1,0,3,2] row_mask:0xf bank_mask:0xf bound_ctrl:1
	ds_read_b128 v[130:133], v167 offset:29568
	ds_read_b128 v[146:149], v114 offset:54144
	v_add_f32_dpp v151, v151, v151 quad_perm:[2,3,0,1] row_mask:0xf bank_mask:0xf bound_ctrl:1
	ds_read_b32 v160, v115 offset:1280
	ds_write_b32 v116, v158 offset:6144
	v_add_f32_dpp v151, v151, v151 row_half_mirror row_mask:0xf bank_mask:0xf bound_ctrl:1
	v_cvt_pkrtz_f16_f32 v152, -v151, -v151
	v_pk_mul_f16 v153, v152, v68
	v_pk_mul_f16 v154, v152, v69
	v_pk_mul_f16 v155, v152, v70
	v_pk_mul_f16 v156, v152, v71
	v_pk_fma_f16 v153, v85, v64, v153
	v_pk_fma_f16 v154, v85, v65, v154
	v_pk_fma_f16 v155, v85, v66, v155
	v_pk_fma_f16 v156, v85, v67, v156
	v_pk_fma_f16 v127, v127, v60, v153
	v_pk_fma_f16 v126, v126, v61, v154
	v_pk_fma_f16 v125, v125, v62, v155
	v_pk_fma_f16 v124, v124, v63, v156
	v_dot2_f32_f16 v157, v127, v56, 0
	v_dot2_f32_f16 v157, v126, v57, v157
	v_dot2_f32_f16 v157, v125, v58, v157
	v_dot2_f32_f16 v157, v124, v59, v157
	s_waitcnt lgkmcnt(0)
	v_dot2_f32_f16 v151, v127, v134, 0
	v_dot2_f32_f16 v151, v126, v135, v151
	v_dot2_f32_f16 v151, v125, v136, v151
	v_dot2_f32_f16 v151, v124, v137, v151
	ds_read_b128 v[72:75], v114 offset:41984
	ds_read_b128 v[68:71], v114 offset:46080
	ds_read_b128 v[64:67], v114 offset:50176
	v_add_f32_dpp v151, v151, v151 quad_perm:[1,0,3,2] row_mask:0xf bank_mask:0xf bound_ctrl:1
	ds_read_b128 v[60:63], v167 offset:29696
	ds_read_b128 v[56:59], v114 offset:54272
	v_add_f32_dpp v151, v151, v151 quad_perm:[2,3,0,1] row_mask:0xf bank_mask:0xf bound_ctrl:1
	ds_read_b32 v85, v115 offset:1536
	ds_write_b32 v116, v157 offset:8192
	v_add_f32_dpp v151, v151, v151 row_half_mirror row_mask:0xf bank_mask:0xf bound_ctrl:1
	v_cvt_pkrtz_f16_f32 v152, -v151, -v151
	v_pk_mul_f16 v153, v152, v138
	v_pk_mul_f16 v154, v152, v139
	v_pk_mul_f16 v155, v152, v140
	v_pk_mul_f16 v156, v152, v141
	v_pk_fma_f16 v153, v160, v142, v153
	v_pk_fma_f16 v154, v160, v143, v154
	v_pk_fma_f16 v155, v160, v144, v155
	v_pk_fma_f16 v156, v160, v145, v156
	v_pk_fma_f16 v127, v127, v130, v153
	v_pk_fma_f16 v126, v126, v131, v154
	v_pk_fma_f16 v125, v125, v132, v155
	v_pk_fma_f16 v124, v124, v133, v156
	v_dot2_f32_f16 v158, v127, v146, 0
	v_dot2_f32_f16 v158, v126, v147, v158
	v_dot2_f32_f16 v158, v125, v148, v158
	v_dot2_f32_f16 v158, v124, v149, v158
	s_waitcnt lgkmcnt(0)
	v_dot2_f32_f16 v151, v127, v72, 0
	v_dot2_f32_f16 v151, v126, v73, v151
	v_dot2_f32_f16 v151, v125, v74, v151
	v_dot2_f32_f16 v151, v124, v75, v151
	ds_read_b128 v[134:137], v114 offset:42112
	ds_read_b128 v[138:141], v114 offset:46208
	ds_read_b128 v[142:145], v114 offset:50304
	v_add_f32_dpp v151, v151, v151 quad_perm:[1,0,3,2] row_mask:0xf bank_mask:0xf bound_ctrl:1
	ds_read_b128 v[130:133], v167 offset:29824
	ds_read_b128 v[146:149], v114 offset:54400
	v_add_f32_dpp v151, v151, v151 quad_perm:[2,3,0,1] row_mask:0xf bank_mask:0xf bound_ctrl:1
	ds_read_b32 v160, v115 offset:1792
	ds_write_b32 v116, v158 offset:10240
	v_add_f32_dpp v151, v151, v151 row_half_mirror row_mask:0xf bank_mask:0xf bound_ctrl:1
	v_cvt_pkrtz_f16_f32 v152, -v151, -v151
	v_pk_mul_f16 v153, v152, v68
	v_pk_mul_f16 v154, v152, v69
	v_pk_mul_f16 v155, v152, v70
	v_pk_mul_f16 v156, v152, v71
	v_pk_fma_f16 v153, v85, v64, v153
	v_pk_fma_f16 v154, v85, v65, v154
	v_pk_fma_f16 v155, v85, v66, v155
	v_pk_fma_f16 v156, v85, v67, v156
	v_pk_fma_f16 v127, v127, v60, v153
	v_pk_fma_f16 v126, v126, v61, v154
	v_pk_fma_f16 v125, v125, v62, v155
	v_pk_fma_f16 v124, v124, v63, v156
	v_dot2_f32_f16 v157, v127, v56, 0
	v_dot2_f32_f16 v157, v126, v57, v157
	v_dot2_f32_f16 v157, v125, v58, v157
	v_dot2_f32_f16 v157, v124, v59, v157
	s_waitcnt lgkmcnt(0)
	v_dot2_f32_f16 v151, v127, v134, 0
	v_dot2_f32_f16 v151, v126, v135, v151
	v_dot2_f32_f16 v151, v125, v136, v151
	v_dot2_f32_f16 v151, v124, v137, v151
	ds_read_b128 v[72:75], v114 offset:42240
	ds_read_b128 v[68:71], v114 offset:46336
	ds_read_b128 v[64:67], v114 offset:50432
	v_add_f32_dpp v151, v151, v151 quad_perm:[1,0,3,2] row_mask:0xf bank_mask:0xf bound_ctrl:1
	ds_read_b128 v[60:63], v167 offset:29952
	ds_read_b128 v[56:59], v114 offset:54528
	v_add_f32_dpp v151, v151, v151 quad_perm:[2,3,0,1] row_mask:0xf bank_mask:0xf bound_ctrl:1
	ds_read_b32 v85, v115 offset:2048
	ds_write_b32 v116, v157 offset:12288
	v_add_f32_dpp v151, v151, v151 row_half_mirror row_mask:0xf bank_mask:0xf bound_ctrl:1
	v_cvt_pkrtz_f16_f32 v152, -v151, -v151
	v_pk_mul_f16 v153, v152, v138
	v_pk_mul_f16 v154, v152, v139
	v_pk_mul_f16 v155, v152, v140
	v_pk_mul_f16 v156, v152, v141
	v_pk_fma_f16 v153, v160, v142, v153
	v_pk_fma_f16 v154, v160, v143, v154
	v_pk_fma_f16 v155, v160, v144, v155
	v_pk_fma_f16 v156, v160, v145, v156
	v_pk_fma_f16 v127, v127, v130, v153
	v_pk_fma_f16 v126, v126, v131, v154
	v_pk_fma_f16 v125, v125, v132, v155
	v_pk_fma_f16 v124, v124, v133, v156
	v_dot2_f32_f16 v158, v127, v146, 0
	v_dot2_f32_f16 v158, v126, v147, v158
	v_dot2_f32_f16 v158, v125, v148, v158
	v_dot2_f32_f16 v158, v124, v149, v158
	s_waitcnt lgkmcnt(0)
	v_dot2_f32_f16 v151, v127, v72, 0
	v_dot2_f32_f16 v151, v126, v73, v151
	v_dot2_f32_f16 v151, v125, v74, v151
	v_dot2_f32_f16 v151, v124, v75, v151
	ds_read_b128 v[134:137], v114 offset:42368
	ds_read_b128 v[138:141], v114 offset:46464
	ds_read_b128 v[142:145], v114 offset:50560
	v_add_f32_dpp v151, v151, v151 quad_perm:[1,0,3,2] row_mask:0xf bank_mask:0xf bound_ctrl:1
	ds_read_b128 v[130:133], v167 offset:30080
	ds_read_b128 v[146:149], v114 offset:54656
	v_add_f32_dpp v151, v151, v151 quad_perm:[2,3,0,1] row_mask:0xf bank_mask:0xf bound_ctrl:1
	ds_read_b32 v160, v115 offset:2304
	ds_write_b32 v116, v158 offset:14336
	v_add_f32_dpp v151, v151, v151 row_half_mirror row_mask:0xf bank_mask:0xf bound_ctrl:1
	v_cvt_pkrtz_f16_f32 v152, -v151, -v151
	v_pk_mul_f16 v153, v152, v68
	v_pk_mul_f16 v154, v152, v69
	v_pk_mul_f16 v155, v152, v70
	v_pk_mul_f16 v156, v152, v71
	v_pk_fma_f16 v153, v85, v64, v153
	v_pk_fma_f16 v154, v85, v65, v154
	v_pk_fma_f16 v155, v85, v66, v155
	v_pk_fma_f16 v156, v85, v67, v156
	v_pk_fma_f16 v127, v127, v60, v153
	v_pk_fma_f16 v126, v126, v61, v154
	v_pk_fma_f16 v125, v125, v62, v155
	v_pk_fma_f16 v124, v124, v63, v156
	v_dot2_f32_f16 v157, v127, v56, 0
	v_dot2_f32_f16 v157, v126, v57, v157
	v_dot2_f32_f16 v157, v125, v58, v157
	v_dot2_f32_f16 v157, v124, v59, v157
	s_waitcnt lgkmcnt(0)
	v_dot2_f32_f16 v151, v127, v134, 0
	v_dot2_f32_f16 v151, v126, v135, v151
	v_dot2_f32_f16 v151, v125, v136, v151
	v_dot2_f32_f16 v151, v124, v137, v151
	ds_read_b128 v[72:75], v114 offset:42496
	ds_read_b128 v[68:71], v114 offset:46592
	ds_read_b128 v[64:67], v114 offset:50688
	v_add_f32_dpp v151, v151, v151 quad_perm:[1,0,3,2] row_mask:0xf bank_mask:0xf bound_ctrl:1
	ds_read_b128 v[60:63], v167 offset:30208
	ds_read_b128 v[56:59], v114 offset:54784
	v_add_f32_dpp v151, v151, v151 quad_perm:[2,3,0,1] row_mask:0xf bank_mask:0xf bound_ctrl:1
	ds_read_b32 v85, v115 offset:2560
	ds_write_b32 v116, v157 offset:16384
	v_add_f32_dpp v151, v151, v151 row_half_mirror row_mask:0xf bank_mask:0xf bound_ctrl:1
	v_cvt_pkrtz_f16_f32 v152, -v151, -v151
	v_pk_mul_f16 v153, v152, v138
	v_pk_mul_f16 v154, v152, v139
	v_pk_mul_f16 v155, v152, v140
	v_pk_mul_f16 v156, v152, v141
	v_pk_fma_f16 v153, v160, v142, v153
	v_pk_fma_f16 v154, v160, v143, v154
	v_pk_fma_f16 v155, v160, v144, v155
	v_pk_fma_f16 v156, v160, v145, v156
	v_pk_fma_f16 v127, v127, v130, v153
	v_pk_fma_f16 v126, v126, v131, v154
	v_pk_fma_f16 v125, v125, v132, v155
	v_pk_fma_f16 v124, v124, v133, v156
	v_dot2_f32_f16 v158, v127, v146, 0
	v_dot2_f32_f16 v158, v126, v147, v158
	v_dot2_f32_f16 v158, v125, v148, v158
	v_dot2_f32_f16 v158, v124, v149, v158
	s_waitcnt lgkmcnt(0)
	v_dot2_f32_f16 v151, v127, v72, 0
	v_dot2_f32_f16 v151, v126, v73, v151
	v_dot2_f32_f16 v151, v125, v74, v151
	v_dot2_f32_f16 v151, v124, v75, v151
	ds_read_b128 v[134:137], v114 offset:42624
	ds_read_b128 v[138:141], v114 offset:46720
	ds_read_b128 v[142:145], v114 offset:50816
	v_add_f32_dpp v151, v151, v151 quad_perm:[1,0,3,2] row_mask:0xf bank_mask:0xf bound_ctrl:1
	ds_read_b128 v[130:133], v167 offset:30336
	ds_read_b128 v[146:149], v114 offset:54912
	v_add_f32_dpp v151, v151, v151 quad_perm:[2,3,0,1] row_mask:0xf bank_mask:0xf bound_ctrl:1
	ds_read_b32 v160, v115 offset:2816
	ds_write_b32 v116, v158 offset:18432
	v_add_f32_dpp v151, v151, v151 row_half_mirror row_mask:0xf bank_mask:0xf bound_ctrl:1
	v_cvt_pkrtz_f16_f32 v152, -v151, -v151
	v_pk_mul_f16 v153, v152, v68
	v_pk_mul_f16 v154, v152, v69
	v_pk_mul_f16 v155, v152, v70
	v_pk_mul_f16 v156, v152, v71
	v_pk_fma_f16 v153, v85, v64, v153
	v_pk_fma_f16 v154, v85, v65, v154
	v_pk_fma_f16 v155, v85, v66, v155
	v_pk_fma_f16 v156, v85, v67, v156
	v_pk_fma_f16 v127, v127, v60, v153
	v_pk_fma_f16 v126, v126, v61, v154
	v_pk_fma_f16 v125, v125, v62, v155
	v_pk_fma_f16 v124, v124, v63, v156
	v_dot2_f32_f16 v157, v127, v56, 0
	v_dot2_f32_f16 v157, v126, v57, v157
	v_dot2_f32_f16 v157, v125, v58, v157
	v_dot2_f32_f16 v157, v124, v59, v157
	s_waitcnt lgkmcnt(0)
	v_dot2_f32_f16 v151, v127, v134, 0
	v_dot2_f32_f16 v151, v126, v135, v151
	v_dot2_f32_f16 v151, v125, v136, v151
	v_dot2_f32_f16 v151, v124, v137, v151
	ds_read_b128 v[72:75], v114 offset:42752
	ds_read_b128 v[68:71], v114 offset:46848
	ds_read_b128 v[64:67], v114 offset:50944
	v_add_f32_dpp v151, v151, v151 quad_perm:[1,0,3,2] row_mask:0xf bank_mask:0xf bound_ctrl:1
	ds_read_b128 v[60:63], v167 offset:30464
	ds_read_b128 v[56:59], v114 offset:55040
	v_add_f32_dpp v151, v151, v151 quad_perm:[2,3,0,1] row_mask:0xf bank_mask:0xf bound_ctrl:1
	ds_read_b32 v85, v115 offset:3072
	ds_write_b32 v116, v157 offset:20480
	v_add_f32_dpp v151, v151, v151 row_half_mirror row_mask:0xf bank_mask:0xf bound_ctrl:1
	v_cvt_pkrtz_f16_f32 v152, -v151, -v151
	v_pk_mul_f16 v153, v152, v138
	v_pk_mul_f16 v154, v152, v139
	v_pk_mul_f16 v155, v152, v140
	v_pk_mul_f16 v156, v152, v141
	v_pk_fma_f16 v153, v160, v142, v153
	v_pk_fma_f16 v154, v160, v143, v154
	v_pk_fma_f16 v155, v160, v144, v155
	v_pk_fma_f16 v156, v160, v145, v156
	v_pk_fma_f16 v127, v127, v130, v153
	v_pk_fma_f16 v126, v126, v131, v154
	v_pk_fma_f16 v125, v125, v132, v155
	v_pk_fma_f16 v124, v124, v133, v156
	v_dot2_f32_f16 v158, v127, v146, 0
	v_dot2_f32_f16 v158, v126, v147, v158
	v_dot2_f32_f16 v158, v125, v148, v158
	v_dot2_f32_f16 v158, v124, v149, v158
	s_waitcnt lgkmcnt(0)
	v_dot2_f32_f16 v151, v127, v72, 0
	v_dot2_f32_f16 v151, v126, v73, v151
	v_dot2_f32_f16 v151, v125, v74, v151
	v_dot2_f32_f16 v151, v124, v75, v151
	ds_read_b128 v[134:137], v114 offset:42880
	ds_read_b128 v[138:141], v114 offset:46976
	ds_read_b128 v[142:145], v114 offset:51072
	v_add_f32_dpp v151, v151, v151 quad_perm:[1,0,3,2] row_mask:0xf bank_mask:0xf bound_ctrl:1
	ds_read_b128 v[130:133], v167 offset:30592
	ds_read_b128 v[146:149], v114 offset:55168
	v_add_f32_dpp v151, v151, v151 quad_perm:[2,3,0,1] row_mask:0xf bank_mask:0xf bound_ctrl:1
	ds_read_b32 v160, v115 offset:3328
	ds_write_b32 v116, v158 offset:22528
	v_add_f32_dpp v151, v151, v151 row_half_mirror row_mask:0xf bank_mask:0xf bound_ctrl:1
	v_cvt_pkrtz_f16_f32 v152, -v151, -v151
	v_pk_mul_f16 v153, v152, v68
	v_pk_mul_f16 v154, v152, v69
	v_pk_mul_f16 v155, v152, v70
	v_pk_mul_f16 v156, v152, v71
	v_pk_fma_f16 v153, v85, v64, v153
	v_pk_fma_f16 v154, v85, v65, v154
	v_pk_fma_f16 v155, v85, v66, v155
	v_pk_fma_f16 v156, v85, v67, v156
	v_pk_fma_f16 v127, v127, v60, v153
	v_pk_fma_f16 v126, v126, v61, v154
	v_pk_fma_f16 v125, v125, v62, v155
	v_pk_fma_f16 v124, v124, v63, v156
	v_dot2_f32_f16 v157, v127, v56, 0
	v_dot2_f32_f16 v157, v126, v57, v157
	v_dot2_f32_f16 v157, v125, v58, v157
	v_dot2_f32_f16 v157, v124, v59, v157
	s_waitcnt lgkmcnt(0)
	v_dot2_f32_f16 v151, v127, v134, 0
	v_dot2_f32_f16 v151, v126, v135, v151
	v_dot2_f32_f16 v151, v125, v136, v151
	v_dot2_f32_f16 v151, v124, v137, v151
	ds_read_b128 v[72:75], v114 offset:43008
	ds_read_b128 v[68:71], v114 offset:47104
	ds_read_b128 v[64:67], v114 offset:51200
	v_add_f32_dpp v151, v151, v151 quad_perm:[1,0,3,2] row_mask:0xf bank_mask:0xf bound_ctrl:1
	ds_read_b128 v[60:63], v167 offset:30720
	ds_read_b128 v[56:59], v114 offset:55296
	v_add_f32_dpp v151, v151, v151 quad_perm:[2,3,0,1] row_mask:0xf bank_mask:0xf bound_ctrl:1
	ds_read_b32 v85, v115 offset:3584
	ds_write_b32 v116, v157 offset:24576
	v_add_f32_dpp v151, v151, v151 row_half_mirror row_mask:0xf bank_mask:0xf bound_ctrl:1
	v_cvt_pkrtz_f16_f32 v152, -v151, -v151
	v_pk_mul_f16 v153, v152, v138
	v_pk_mul_f16 v154, v152, v139
	v_pk_mul_f16 v155, v152, v140
	v_pk_mul_f16 v156, v152, v141
	v_pk_fma_f16 v153, v160, v142, v153
	v_pk_fma_f16 v154, v160, v143, v154
	v_pk_fma_f16 v155, v160, v144, v155
	v_pk_fma_f16 v156, v160, v145, v156
	v_pk_fma_f16 v127, v127, v130, v153
	v_pk_fma_f16 v126, v126, v131, v154
	v_pk_fma_f16 v125, v125, v132, v155
	v_pk_fma_f16 v124, v124, v133, v156
	v_dot2_f32_f16 v158, v127, v146, 0
	v_dot2_f32_f16 v158, v126, v147, v158
	v_dot2_f32_f16 v158, v125, v148, v158
	v_dot2_f32_f16 v158, v124, v149, v158
	s_waitcnt lgkmcnt(0)
	v_dot2_f32_f16 v151, v127, v72, 0
	v_dot2_f32_f16 v151, v126, v73, v151
	v_dot2_f32_f16 v151, v125, v74, v151
	v_dot2_f32_f16 v151, v124, v75, v151
	ds_read_b128 v[134:137], v114 offset:43136
	ds_read_b128 v[138:141], v114 offset:47232
	ds_read_b128 v[142:145], v114 offset:51328
	v_add_f32_dpp v151, v151, v151 quad_perm:[1,0,3,2] row_mask:0xf bank_mask:0xf bound_ctrl:1
	ds_read_b128 v[130:133], v167 offset:30848
	ds_read_b128 v[146:149], v114 offset:55424
	v_add_f32_dpp v151, v151, v151 quad_perm:[2,3,0,1] row_mask:0xf bank_mask:0xf bound_ctrl:1
	ds_read_b32 v160, v115 offset:3840
	ds_write_b32 v116, v158 offset:26624
	v_add_f32_dpp v151, v151, v151 row_half_mirror row_mask:0xf bank_mask:0xf bound_ctrl:1
	v_cvt_pkrtz_f16_f32 v152, -v151, -v151
	v_pk_mul_f16 v153, v152, v68
	v_pk_mul_f16 v154, v152, v69
	v_pk_mul_f16 v155, v152, v70
	v_pk_mul_f16 v156, v152, v71
	v_pk_fma_f16 v153, v85, v64, v153
	v_pk_fma_f16 v154, v85, v65, v154
	v_pk_fma_f16 v155, v85, v66, v155
	v_pk_fma_f16 v156, v85, v67, v156
	v_pk_fma_f16 v127, v127, v60, v153
	v_pk_fma_f16 v126, v126, v61, v154
	v_pk_fma_f16 v125, v125, v62, v155
	v_pk_fma_f16 v124, v124, v63, v156
	v_dot2_f32_f16 v157, v127, v56, 0
	v_dot2_f32_f16 v157, v126, v57, v157
	v_dot2_f32_f16 v157, v125, v58, v157
	v_dot2_f32_f16 v157, v124, v59, v157
	s_waitcnt lgkmcnt(0)
	v_dot2_f32_f16 v151, v127, v134, 0
	v_dot2_f32_f16 v151, v126, v135, v151
	v_dot2_f32_f16 v151, v125, v136, v151
	v_dot2_f32_f16 v151, v124, v137, v151
	s_nop 2
	v_add_f32_dpp v151, v151, v151 quad_perm:[1,0,3,2] row_mask:0xf bank_mask:0xf bound_ctrl:1
	s_nop 1
	v_add_f32_dpp v151, v151, v151 quad_perm:[2,3,0,1] row_mask:0xf bank_mask:0xf bound_ctrl:1
	s_nop 0
	ds_write_b32 v116, v157 offset:28672
	v_add_f32_dpp v151, v151, v151 row_half_mirror row_mask:0xf bank_mask:0xf bound_ctrl:1
	v_cvt_pkrtz_f16_f32 v152, -v151, -v151
	v_pk_mul_f16 v153, v152, v138
	v_pk_mul_f16 v154, v152, v139
	v_pk_mul_f16 v155, v152, v140
	v_pk_mul_f16 v156, v152, v141
	v_pk_fma_f16 v153, v160, v142, v153
	v_pk_fma_f16 v154, v160, v143, v154
	v_pk_fma_f16 v155, v160, v144, v155
	v_pk_fma_f16 v156, v160, v145, v156
	v_pk_fma_f16 v127, v127, v130, v153
	v_pk_fma_f16 v126, v126, v131, v154
	v_pk_fma_f16 v125, v125, v132, v155
	v_pk_fma_f16 v124, v124, v133, v156
	v_dot2_f32_f16 v158, v127, v146, 0
	v_dot2_f32_f16 v158, v126, v147, v158
	v_dot2_f32_f16 v158, v125, v148, v158
	v_dot2_f32_f16 v158, v124, v149, v158
	s_nop 2
	ds_write_b32 v116, v158 offset:30720
	s_xor_b32 s100, s100, 0xe100
	s_cmpk_lg_i32 s30, 0x80
	s_cbranch_scc0 .LBB0_1250
	s_mov_b32 s4, s30
	s_and_saveexec_b64 s[18:19], s[10:11]
	s_cbranch_execnz .LBB0_1229
	s_branch .LBB0_1230
